# final RMSNorm loop pipelined + SGU unit: contiguous v-block loads and row-rsqrt work moved behind all loads
# baseline (speedup 1.0000x reference)
.LBB0_680:
	s_or_b64 exec, exec, s[6:7]
	s_bfe_u32 s7, s9, 0x20006
	s_ashr_i32 s9, s9, 8
	s_lshl_b32 s6, s8, 2
	s_or_b32 s11, s7, s6
	s_lshl_b32 s6, s9, 6
	s_lshl_b32 s36, s11, 7
	s_ashr_i32 s8, s6, 31
	v_and_b32_e32 v220, 31, v20
	s_add_u32 s12, s36, s6
	v_and_b32_e32 v49, 0x7f, v20
	v_bfe_u32 v22, v20, 5, 1
	s_addc_u32 s8, 0, s8
	v_or_b32_e32 v20, s12, v220
	v_readlane_b32 s12, v249, 34
	v_mov_b32_e32 v21, s8
	v_lshlrev_b32_e32 v62, 4, v22
	v_mov_b32_e32 v63, v197
	v_readlane_b32 s13, v249, 35
	v_lshlrev_b32_e32 v196, 3, v22
	v_lshlrev_b64 v[20:21], 8, v[20:21]
	v_lshl_add_u64 v[22:23], s[12:13], 0, v[62:63]
	v_lshl_add_u64 v[64:65], v[22:23], 0, v[20:21]
	s_movk_i32 s8, 0x2000
	global_load_dwordx4 v[40:43], v[64:65], off
	global_load_dwordx4 v[140:143], v[64:65], off offset:32
	global_load_dwordx4 v[136:139], v[64:65], off offset:64
	global_load_dwordx4 v[132:135], v[64:65], off offset:96
	global_load_dwordx4 v[128:131], v[64:65], off offset:128
	global_load_dwordx4 v[28:31], v[64:65], off offset:160
	global_load_dwordx4 v[24:27], v[64:65], off offset:192
	global_load_dwordx4 v[20:23], v[64:65], off offset:224
	v_add_co_u32_e32 v64, vcc, s8, v64
	s_and_b32 s8, s2, 0x3fffffe
	s_nop 0
	v_addc_co_u32_e32 v65, vcc, 0, v65, vcc
	s_add_i32 s9, s9, s8
	global_load_dwordx4 v[124:127], v[64:65], off
	global_load_dwordx4 v[120:123], v[64:65], off offset:32
	global_load_dwordx4 v[116:119], v[64:65], off offset:64
	global_load_dwordx4 v[112:115], v[64:65], off offset:96
	global_load_dwordx4 v[108:111], v[64:65], off offset:128
	global_load_dwordx4 v[104:107], v[64:65], off offset:160
	global_load_dwordx4 v[100:103], v[64:65], off offset:192
	global_load_dwordx4 v[96:99], v[64:65], off offset:224
	v_lshl_or_b32 v51, s9, 6, v220
	v_mov_b64_e32 v[64:65], s[82:83]
	v_mad_i64_i32 v[66:67], s[8:9], v51, s94, v[64:65]
	v_or_b32_e32 v51, 32, v51
	v_mad_i64_i32 v[64:65], s[8:9], v51, s94, v[64:65]
	s_lshl_b32 s8, s11, 8
	v_readlane_b32 s9, v249, 38
	v_lshl_add_u64 v[66:67], v[66:67], 0, s[36:37]
	v_lshl_add_u64 v[64:65], v[64:65], 0, s[36:37]
	s_add_u32 s8, s9, s8
	v_readlane_b32 s9, v249, 39
	v_lshl_add_u64 v[66:67], v[66:67], 0, v[196:197]
	v_lshl_add_u64 v[64:65], v[64:65], 0, v[196:197]
	s_addc_u32 s9, s9, 0
	global_load_dwordx2 v[174:175], v[66:67], off offset:1536
	global_load_dwordx2 v[172:173], v[66:67], off offset:1552
	global_load_dwordx2 v[170:171], v[66:67], off offset:1568
	global_load_dwordx2 v[168:169], v[66:67], off offset:1584
	global_load_dwordx2 v[166:167], v[66:67], off offset:1600
	global_load_dwordx2 v[164:165], v[66:67], off offset:1616
	global_load_dwordx2 v[162:163], v[66:67], off offset:1632
	global_load_dwordx2 v[160:161], v[66:67], off offset:1648
	global_load_dwordx2 v[158:159], v[64:65], off offset:1536
	global_load_dwordx2 v[156:157], v[64:65], off offset:1552
	global_load_dwordx2 v[154:155], v[64:65], off offset:1568
	global_load_dwordx2 v[152:153], v[64:65], off offset:1584
	global_load_dwordx2 v[150:151], v[64:65], off offset:1600
	global_load_dwordx2 v[148:149], v[64:65], off offset:1616
	global_load_dwordx2 v[146:147], v[64:65], off offset:1632
	global_load_dwordx2 v[144:145], v[64:65], off offset:1648
	global_load_dwordx4 v[92:95], v62, s[8:9]
	global_load_dwordx4 v[88:91], v62, s[8:9] offset:32
	global_load_dwordx4 v[84:87], v62, s[8:9] offset:64
	global_load_dwordx4 v[80:83], v62, s[8:9] offset:96
	global_load_dwordx4 v[76:79], v62, s[8:9] offset:128
	global_load_dwordx4 v[72:75], v62, s[8:9] offset:160
	global_load_dwordx4 v[68:71], v62, s[8:9] offset:192
	global_load_dwordx4 v[64:67], v62, s[8:9] offset:224
	s_add_i32 s8, s36, s6
	v_or_b32_e32 v178, s8, v220
	v_readlane_b32 s8, v249, 36
	v_ashrrev_i32_e32 v179, 31, v178
	v_readlane_b32 s9, v249, 37
	v_lshl_add_u32 v51, v49, 2, 0
	v_lshlrev_b32_e32 v49, 1, v49
	v_lshl_add_u64 v[180:181], v[178:179], 2, s[8:9]
	global_load_dword v178, v[180:181], off
	global_load_dword v177, v[180:181], off offset:128
	v_readfirstlane_b32 vcc_lo, v199
	s_cmp_lt_u32 vcc_lo, 0x80
	s_cbranch_scc0 .Lsgu_norv
	s_waitcnt vmcnt(50)
	v_add_f32_e32 v234, v234, v235
	v_add_f32_e32 v236, v236, v237
	v_add_f32_e32 v238, v238, v239
	v_add_f32_e32 v240, v240, v241
	v_add_f32_e32 v242, v242, v243
	v_add_f32_e32 v244, v244, v245
	v_add_f32_e32 v254, v254, v255
	v_add_f32_e32 v246, v246, v247
	v_add_f32_e32 v234, v234, v236
	v_add_f32_e32 v238, v238, v240
	v_add_f32_e32 v242, v242, v244
	v_add_f32_e32 v254, v254, v246
	v_add_f32_e32 v234, v234, v238
	v_add_f32_e32 v242, v242, v254
	v_add_f32_e32 v234, v234, v242
	v_fmamk_f32 v234, v234, 0x3b000000, v198
	v_cmp_gt_f32_e32 vcc, s39, v234
	v_mul_f32_e32 v235, 0x4b800000, v234
	s_nop 0
	v_cndmask_b32_e32 v234, v234, v235, vcc
	v_rsq_f32_e32 v234, v234
	s_nop 0
	v_mul_f32_e32 v235, 0x45800000, v234
	v_cndmask_b32_e32 v234, v234, v235, vcc
	v_lshl_add_u32 v235, v199, 2, 0
	ds_write_b32 v235, v234
.Lsgu_norv:
	s_waitcnt vmcnt(0) lgkmcnt(0)
	s_barrier
	ds_read_b32 v53, v51
	v_sub_u32_e32 v180, v51, v49
	v_lshlrev_b32_e32 v49, 16, v44
	v_and_b32_e32 v44, 0xffff0000, v44
	s_movk_i32 s11, 0x110
	s_waitcnt lgkmcnt(0)
	v_mul_f32_e32 v44, v53, v44
	v_mad_u64_u32 v[182:183], s[8:9], v176, s11, v[180:181]
	v_mul_f32_e32 v49, v53, v49
	v_cvt_pk_bf16_f32 v44, v49, v44
	ds_write_b16 v182, v44 offset:1024
	ds_write_b16_d16_hi v182, v44 offset:1296
	v_lshlrev_b32_e32 v44, 16, v45
	v_mul_f32_e32 v44, v53, v44
	v_and_b32_e32 v45, 0xffff0000, v45
	v_mul_f32_e32 v45, v53, v45
	v_cvt_pk_bf16_f32 v44, v44, v45
	ds_write_b16 v182, v44 offset:1568
	ds_write_b16_d16_hi v182, v44 offset:1840
	v_lshlrev_b32_e32 v44, 16, v46
	v_mul_f32_e32 v44, v53, v44
	v_and_b32_e32 v45, 0xffff0000, v46
	v_mul_f32_e32 v45, v53, v45
	v_cvt_pk_bf16_f32 v44, v44, v45
	ds_write_b16 v182, v44 offset:2112
	ds_write_b16_d16_hi v182, v44 offset:2384
	v_lshlrev_b32_e32 v44, 16, v47
	v_mul_f32_e32 v44, v53, v44
	v_and_b32_e32 v45, 0xffff0000, v47
	v_mul_f32_e32 v45, v53, v45
	v_cvt_pk_bf16_f32 v44, v44, v45
	ds_read_b32 v46, v51
	ds_write_b16 v182, v44 offset:2656
	ds_write_b16_d16_hi v182, v44 offset:2928
	v_mad_u64_u32 v[44:45], s[8:9], v60, s11, v[180:181]
	v_lshlrev_b32_e32 v45, 16, v36
	v_and_b32_e32 v36, 0xffff0000, v36
	s_waitcnt lgkmcnt(2)
	v_mul_f32_e32 v36, v46, v36
	v_mul_f32_e32 v45, v46, v45
	v_cvt_pk_bf16_f32 v36, v45, v36
	ds_write_b16 v44, v36 offset:1024
	ds_write_b16_d16_hi v44, v36 offset:1296
	v_lshlrev_b32_e32 v36, 16, v37
	v_mul_f32_e32 v36, v46, v36
	v_and_b32_e32 v37, 0xffff0000, v37
	v_mul_f32_e32 v37, v46, v37
	v_cvt_pk_bf16_f32 v36, v36, v37
	ds_write_b16 v44, v36 offset:1568
	ds_write_b16_d16_hi v44, v36 offset:1840
	v_lshlrev_b32_e32 v36, 16, v38
	v_mul_f32_e32 v36, v46, v36
	v_and_b32_e32 v37, 0xffff0000, v38
	v_mul_f32_e32 v37, v46, v37
	v_cvt_pk_bf16_f32 v36, v36, v37
	ds_write_b16 v44, v36 offset:2112
	ds_write_b16_d16_hi v44, v36 offset:2384
	v_lshlrev_b32_e32 v36, 16, v39
	v_mul_f32_e32 v36, v46, v36
	v_and_b32_e32 v37, 0xffff0000, v39
	v_mul_f32_e32 v37, v46, v37
	v_cvt_pk_bf16_f32 v36, v36, v37
	ds_read_b32 v38, v51
	ds_write_b16 v44, v36 offset:2656
	ds_write_b16_d16_hi v44, v36 offset:2928
	v_mad_u64_u32 v[36:37], s[8:9], v58, s11, v[180:181]
	v_lshlrev_b32_e32 v37, 16, v32
	v_and_b32_e32 v32, 0xffff0000, v32
	s_waitcnt lgkmcnt(2)
	v_mul_f32_e32 v32, v38, v32
	v_mul_f32_e32 v37, v38, v37
	v_cvt_pk_bf16_f32 v32, v37, v32
	ds_write_b16 v36, v32 offset:1024
	ds_write_b16_d16_hi v36, v32 offset:1296
	v_lshlrev_b32_e32 v32, 16, v33
	v_mul_f32_e32 v32, v38, v32
	v_and_b32_e32 v33, 0xffff0000, v33
	v_mul_f32_e32 v33, v38, v33
	v_cvt_pk_bf16_f32 v32, v32, v33
	ds_write_b16 v36, v32 offset:1568
	ds_write_b16_d16_hi v36, v32 offset:1840
	v_lshlrev_b32_e32 v32, 16, v34
	v_mul_f32_e32 v32, v38, v32
	v_and_b32_e32 v33, 0xffff0000, v34
	v_mul_f32_e32 v33, v38, v33
	v_cvt_pk_bf16_f32 v32, v32, v33
	ds_write_b16 v36, v32 offset:2112
	ds_write_b16_d16_hi v36, v32 offset:2384
	v_lshlrev_b32_e32 v32, 16, v35
	v_mul_f32_e32 v32, v38, v32
	v_and_b32_e32 v33, 0xffff0000, v35
	v_mul_f32_e32 v33, v38, v33
	v_cvt_pk_bf16_f32 v32, v32, v33
	ds_read_b32 v34, v51
	ds_write_b16 v36, v32 offset:2656
	ds_write_b16_d16_hi v36, v32 offset:2928
	v_mad_u64_u32 v[32:33], s[8:9], v56, s11, v[180:181]
	v_lshlrev_b32_e32 v33, 16, v16
	v_and_b32_e32 v16, 0xffff0000, v16
	s_waitcnt lgkmcnt(2)
	v_mul_f32_e32 v16, v34, v16
	v_mul_f32_e32 v33, v34, v33
	v_cvt_pk_bf16_f32 v16, v33, v16
	ds_write_b16 v32, v16 offset:1024
	ds_write_b16_d16_hi v32, v16 offset:1296
	v_lshlrev_b32_e32 v16, 16, v17
	v_mul_f32_e32 v16, v34, v16
	v_and_b32_e32 v17, 0xffff0000, v17
	v_mul_f32_e32 v17, v34, v17
	v_cvt_pk_bf16_f32 v16, v16, v17
	ds_write_b16 v32, v16 offset:1568
	ds_write_b16_d16_hi v32, v16 offset:1840
	v_lshlrev_b32_e32 v16, 16, v18
	v_mul_f32_e32 v16, v34, v16
	v_and_b32_e32 v17, 0xffff0000, v18
	v_mul_f32_e32 v17, v34, v17
	v_cvt_pk_bf16_f32 v16, v16, v17
	ds_write_b16 v32, v16 offset:2112
	ds_write_b16_d16_hi v32, v16 offset:2384
	v_lshlrev_b32_e32 v16, 16, v19
	v_mul_f32_e32 v16, v34, v16
	v_and_b32_e32 v17, 0xffff0000, v19
	v_mul_f32_e32 v17, v34, v17
	v_cvt_pk_bf16_f32 v16, v16, v17
	ds_read_b32 v18, v51
	ds_write_b16 v32, v16 offset:2656
	ds_write_b16_d16_hi v32, v16 offset:2928
	v_mad_u64_u32 v[16:17], s[8:9], v54, s11, v[180:181]
	v_lshlrev_b32_e32 v17, 16, v12
	v_and_b32_e32 v12, 0xffff0000, v12
	s_waitcnt lgkmcnt(2)
	v_mul_f32_e32 v12, v18, v12
	v_mul_f32_e32 v17, v18, v17
	v_cvt_pk_bf16_f32 v12, v17, v12
	ds_write_b16 v16, v12 offset:1024
	ds_write_b16_d16_hi v16, v12 offset:1296
	v_lshlrev_b32_e32 v12, 16, v13
	v_mul_f32_e32 v12, v18, v12
	v_and_b32_e32 v13, 0xffff0000, v13
	v_mul_f32_e32 v13, v18, v13
	v_cvt_pk_bf16_f32 v12, v12, v13
	ds_write_b16 v16, v12 offset:1568
	ds_write_b16_d16_hi v16, v12 offset:1840
	v_lshlrev_b32_e32 v12, 16, v14
	v_mul_f32_e32 v12, v18, v12
	v_and_b32_e32 v13, 0xffff0000, v14
	v_mul_f32_e32 v13, v18, v13
	v_cvt_pk_bf16_f32 v12, v12, v13
	ds_write_b16 v16, v12 offset:2112
	ds_write_b16_d16_hi v16, v12 offset:2384
	v_lshlrev_b32_e32 v12, 16, v15
	v_mul_f32_e32 v12, v18, v12
	v_and_b32_e32 v13, 0xffff0000, v15
	v_mul_f32_e32 v13, v18, v13
	v_cvt_pk_bf16_f32 v12, v12, v13
	ds_read_b32 v14, v51
	ds_write_b16 v16, v12 offset:2656
	ds_write_b16_d16_hi v16, v12 offset:2928
	v_mad_u64_u32 v[12:13], s[8:9], v52, s11, v[180:181]
	v_lshlrev_b32_e32 v13, 16, v8
	v_and_b32_e32 v8, 0xffff0000, v8
	s_waitcnt lgkmcnt(2)
	v_mul_f32_e32 v8, v14, v8
	v_mul_f32_e32 v13, v14, v13
	v_cvt_pk_bf16_f32 v8, v13, v8
	ds_write_b16 v12, v8 offset:1024
	ds_write_b16_d16_hi v12, v8 offset:1296
	v_lshlrev_b32_e32 v8, 16, v9
	v_mul_f32_e32 v8, v14, v8
	v_and_b32_e32 v9, 0xffff0000, v9
	v_mul_f32_e32 v9, v14, v9
	v_cvt_pk_bf16_f32 v8, v8, v9
	ds_write_b16 v12, v8 offset:1568
	ds_write_b16_d16_hi v12, v8 offset:1840
	v_lshlrev_b32_e32 v8, 16, v10
	v_mul_f32_e32 v8, v14, v8
	v_and_b32_e32 v9, 0xffff0000, v10
	v_mul_f32_e32 v9, v14, v9
	v_cvt_pk_bf16_f32 v8, v8, v9
	ds_write_b16 v12, v8 offset:2112
	ds_write_b16_d16_hi v12, v8 offset:2384
	v_lshlrev_b32_e32 v8, 16, v11
	v_mul_f32_e32 v8, v14, v8
	v_and_b32_e32 v9, 0xffff0000, v11
	v_mul_f32_e32 v9, v14, v9
	v_cvt_pk_bf16_f32 v8, v8, v9
	ds_read_b32 v10, v51
	ds_write_b16 v12, v8 offset:2656
	ds_write_b16_d16_hi v12, v8 offset:2928
	v_mad_u64_u32 v[8:9], s[8:9], v50, s11, v[180:181]
	v_lshlrev_b32_e32 v9, 16, v4
	v_and_b32_e32 v4, 0xffff0000, v4
	s_waitcnt lgkmcnt(2)
	v_mul_f32_e32 v4, v10, v4
	v_mul_f32_e32 v9, v10, v9
	v_cvt_pk_bf16_f32 v4, v9, v4
	ds_write_b16 v8, v4 offset:1024
	ds_write_b16_d16_hi v8, v4 offset:1296
	v_lshlrev_b32_e32 v4, 16, v5
	v_mul_f32_e32 v4, v10, v4
	v_and_b32_e32 v5, 0xffff0000, v5
	v_mul_f32_e32 v5, v10, v5
	v_cvt_pk_bf16_f32 v4, v4, v5
	ds_write_b16 v8, v4 offset:1568
	ds_write_b16_d16_hi v8, v4 offset:1840
	v_lshlrev_b32_e32 v4, 16, v6
	v_mul_f32_e32 v4, v10, v4
	v_and_b32_e32 v5, 0xffff0000, v6
	v_mul_f32_e32 v5, v10, v5
	v_cvt_pk_bf16_f32 v4, v4, v5
	ds_write_b16 v8, v4 offset:2112
	ds_write_b16_d16_hi v8, v4 offset:2384
	v_lshlrev_b32_e32 v4, 16, v7
	v_mul_f32_e32 v4, v10, v4
	v_and_b32_e32 v5, 0xffff0000, v7
	v_mul_f32_e32 v5, v10, v5
	v_cvt_pk_bf16_f32 v4, v4, v5
	ds_read_b32 v6, v51
	ds_write_b16 v8, v4 offset:2656
	ds_write_b16_d16_hi v8, v4 offset:2928
	v_mad_u64_u32 v[4:5], s[8:9], v48, s11, v[180:181]
	v_lshlrev_b32_e32 v5, 16, v0
	v_and_b32_e32 v0, 0xffff0000, v0
	s_waitcnt lgkmcnt(2)
	v_mul_f32_e32 v0, v6, v0
	v_mul_f32_e32 v5, v6, v5
	v_cvt_pk_bf16_f32 v0, v5, v0
	ds_write_b16 v4, v0 offset:1024
	ds_write_b16_d16_hi v4, v0 offset:1296
	v_lshlrev_b32_e32 v0, 16, v1
	v_mul_f32_e32 v0, v6, v0
	v_and_b32_e32 v1, 0xffff0000, v1
	v_mul_f32_e32 v1, v6, v1
	v_cvt_pk_bf16_f32 v0, v0, v1
	ds_write_b16 v4, v0 offset:1568
	ds_write_b16_d16_hi v4, v0 offset:1840
	v_lshlrev_b32_e32 v0, 16, v2
	v_mul_f32_e32 v0, v6, v0
	v_and_b32_e32 v1, 0xffff0000, v2
	v_mul_f32_e32 v1, v6, v1
	v_cvt_pk_bf16_f32 v0, v0, v1
	ds_write_b16 v4, v0 offset:2112
	ds_write_b16_d16_hi v4, v0 offset:2384
	v_lshlrev_b32_e32 v0, 16, v3
	v_mul_f32_e32 v0, v6, v0
	v_and_b32_e32 v1, 0xffff0000, v3
	v_mul_f32_e32 v1, v6, v1
	v_cvt_pk_bf16_f32 v0, v0, v1
	ds_write_b16 v4, v0 offset:2656
	ds_write_b16_d16_hi v4, v0 offset:2928
	v_lshl_or_b32 v0, s7, 6, v220
	v_mul_u32_u24_e32 v0, 0x110, v0
	v_add3_u32 v8, 0, v62, v0
	s_waitcnt lgkmcnt(0)
	s_barrier
	ds_read_b128 v[0:3], v8 offset:1024
	ds_read_b128 v[180:183], v8 offset:1056
	ds_read_b128 v[4:7], v8 offset:9728
	ds_read_b128 v[184:187], v8 offset:9760
	s_waitcnt lgkmcnt(3)
	v_mfma_f32_32x32x16_bf16 v[48:63], v[0:3], v[40:43], 0
	v_or_b32_e32 v196, s36, v196
	v_readlane_b32 s12, v251, 1
	v_readlane_b32 s14, v251, 3
	s_add_i32 s2, s2, s14
	v_readlane_b32 s13, v251, 2
	v_readlane_b32 s15, v251, 4
	s_waitcnt lgkmcnt(1)
	v_mfma_f32_32x32x16_bf16 v[32:47], v[4:7], v[40:43], 0
	v_mfma_f32_32x32x16_bf16 v[48:63], v[180:183], v[140:143], v[48:63]
	s_waitcnt lgkmcnt(0)
	v_mfma_f32_32x32x16_bf16 v[32:47], v[184:187], v[140:143], v[32:47]
	ds_read_b128 v[140:143], v8 offset:1088
	ds_read_b128 v[188:191], v8 offset:1120
	ds_read_b128 v[192:195], v8 offset:9792
	ds_read_b128 v[204:207], v8 offset:9824
	s_waitcnt lgkmcnt(3)
	v_mfma_f32_32x32x16_bf16 v[48:63], v[140:143], v[136:139], v[48:63]
	s_waitcnt lgkmcnt(1)
	v_mfma_f32_32x32x16_bf16 v[32:47], v[192:195], v[136:139], v[32:47]
	v_mfma_f32_32x32x16_bf16 v[48:63], v[188:191], v[132:135], v[48:63]
	s_waitcnt lgkmcnt(0)
	v_mfma_f32_32x32x16_bf16 v[32:47], v[204:207], v[132:135], v[32:47]
	ds_read_b128 v[132:135], v8 offset:1152
	ds_read_b128 v[136:139], v8 offset:1184
	ds_read_b128 v[208:211], v8 offset:9856
	ds_read_b128 v[212:215], v8 offset:9888
	s_waitcnt lgkmcnt(3)
	v_mfma_f32_32x32x16_bf16 v[48:63], v[132:135], v[128:131], v[48:63]
	s_waitcnt lgkmcnt(1)
	v_mfma_f32_32x32x16_bf16 v[32:47], v[208:211], v[128:131], v[32:47]
	ds_read_b128 v[128:131], v8 offset:1216
	ds_read_b128 v[216:219], v8 offset:1248
	ds_read_b128 v[226:229], v8 offset:9920
	ds_read_b128 v[230:233], v8 offset:9952
	v_mfma_f32_32x32x16_bf16 v[48:63], v[136:139], v[28:31], v[48:63]
	s_waitcnt lgkmcnt(4)
	v_mfma_f32_32x32x16_bf16 v[32:47], v[212:215], v[28:31], v[32:47]
	s_waitcnt lgkmcnt(3)
	v_mfma_f32_32x32x16_bf16 v[48:63], v[128:131], v[24:27], v[48:63]
	s_waitcnt lgkmcnt(1)
	v_mfma_f32_32x32x16_bf16 v[32:47], v[226:229], v[24:27], v[32:47]
	v_mfma_f32_32x32x16_bf16 v[48:63], v[216:219], v[20:23], v[48:63]
	s_waitcnt lgkmcnt(0)
	v_mfma_f32_32x32x16_bf16 v[32:47], v[230:233], v[20:23], v[32:47]
	s_nop 9
	v_fma_f32 v48, v92, v48, v178
	v_fma_f32 v49, v93, v49, v178
	v_fma_f32 v50, v94, v50, v178
	v_fma_f32 v51, v95, v51, v178
	v_mfma_f32_32x32x16_bf16 v[16:31], v[0:3], v[124:127], 0
	v_fma_f32 v32, v76, v32, v178
	v_fma_f32 v33, v77, v33, v178
	v_fma_f32 v34, v78, v34, v178
	v_fma_f32 v35, v79, v35, v178
	v_mfma_f32_32x32x16_bf16 v[0:15], v[4:7], v[124:127], 0
	v_mfma_f32_32x32x16_bf16 v[16:31], v[180:183], v[120:123], v[16:31]
	v_mfma_f32_32x32x16_bf16 v[0:15], v[184:187], v[120:123], v[0:15]
	v_mfma_f32_32x32x16_bf16 v[16:31], v[140:143], v[116:119], v[16:31]
	v_mfma_f32_32x32x16_bf16 v[0:15], v[192:195], v[116:119], v[0:15]
	v_mfma_f32_32x32x16_bf16 v[16:31], v[188:191], v[112:115], v[16:31]
	v_mfma_f32_32x32x16_bf16 v[0:15], v[204:207], v[112:115], v[0:15]
	v_mfma_f32_32x32x16_bf16 v[16:31], v[132:135], v[108:111], v[16:31]
	v_mfma_f32_32x32x16_bf16 v[0:15], v[208:211], v[108:111], v[0:15]
	v_mfma_f32_32x32x16_bf16 v[16:31], v[136:139], v[104:107], v[16:31]
	v_mfma_f32_32x32x16_bf16 v[0:15], v[212:215], v[104:107], v[0:15]
	v_mfma_f32_32x32x16_bf16 v[16:31], v[128:131], v[100:103], v[16:31]
	v_mfma_f32_32x32x16_bf16 v[0:15], v[226:229], v[100:103], v[0:15]
	v_mfma_f32_32x32x16_bf16 v[16:31], v[216:219], v[96:99], v[16:31]
	v_mfma_f32_32x32x16_bf16 v[0:15], v[230:233], v[96:99], v[0:15]
	v_or_b32_e32 v96, s3, v220
	v_add_u32_e32 v96, s6, v96
	v_ashrrev_i32_e32 v97, 31, v96
	v_lshlrev_b64 v[98:99], 11, v[96:97]
	v_lshlrev_b32_e32 v97, 16, v174
	v_mul_f32_e32 v48, v48, v97
	v_and_b32_e32 v97, 0xffff0000, v174
	v_readlane_b32 s6, v252, 55
	v_mul_f32_e32 v49, v49, v97
	v_lshlrev_b32_e32 v97, 16, v175
	v_readlane_b32 s7, v252, 56
	v_mul_f32_e32 v50, v50, v97
	v_and_b32_e32 v97, 0xffff0000, v175
	v_lshl_add_u64 v[98:99], s[6:7], 0, v[98:99]
	v_mul_f32_e32 v51, v51, v97
	v_cvt_pk_bf16_f32 v48, v48, v49
	v_cvt_pk_bf16_f32 v49, v50, v51
	v_lshl_add_u64 v[50:51], v[98:99], 0, v[196:197]
	global_store_dwordx2 v[50:51], v[48:49], off offset:1024
	v_lshlrev_b32_e32 v48, 16, v172
	v_fma_f32 v49, v88, v52, v178
	v_mul_f32_e32 v48, v49, v48
	v_and_b32_e32 v49, 0xffff0000, v172
	v_fma_f32 v52, v89, v53, v178
	v_mul_f32_e32 v49, v52, v49
	v_lshlrev_b32_e32 v52, 16, v173
	v_fma_f32 v53, v90, v54, v178
	v_mul_f32_e32 v52, v53, v52
	v_and_b32_e32 v53, 0xffff0000, v173
	v_fma_f32 v54, v91, v55, v178
	v_mul_f32_e32 v53, v54, v53
	v_cvt_pk_bf16_f32 v48, v48, v49
	v_cvt_pk_bf16_f32 v49, v52, v53
	global_store_dwordx2 v[50:51], v[48:49], off offset:1040
	v_lshlrev_b32_e32 v48, 16, v170
	v_fma_f32 v49, v84, v56, v178
	v_mul_f32_e32 v48, v49, v48
	v_and_b32_e32 v49, 0xffff0000, v170
	v_fma_f32 v52, v85, v57, v178
	v_mul_f32_e32 v49, v52, v49
	v_lshlrev_b32_e32 v52, 16, v171
	v_fma_f32 v53, v86, v58, v178
	v_mul_f32_e32 v52, v53, v52
	v_and_b32_e32 v53, 0xffff0000, v171
	v_fma_f32 v54, v87, v59, v178
	v_mul_f32_e32 v53, v54, v53
	v_cvt_pk_bf16_f32 v48, v48, v49
	v_cvt_pk_bf16_f32 v49, v52, v53
	global_store_dwordx2 v[50:51], v[48:49], off offset:1056
	v_lshlrev_b32_e32 v48, 16, v168
	v_fma_f32 v49, v80, v60, v178
	v_mul_f32_e32 v48, v49, v48
	v_and_b32_e32 v49, 0xffff0000, v168
	v_fma_f32 v52, v81, v61, v178
	v_mul_f32_e32 v49, v52, v49
	v_lshlrev_b32_e32 v52, 16, v169
	v_fma_f32 v53, v82, v62, v178
	v_mul_f32_e32 v52, v53, v52
	v_and_b32_e32 v53, 0xffff0000, v169
	v_fma_f32 v54, v83, v63, v178
	v_cvt_pk_bf16_f32 v48, v48, v49
	v_mul_f32_e32 v53, v54, v53
	v_cvt_pk_bf16_f32 v49, v52, v53
	global_store_dwordx2 v[50:51], v[48:49], off offset:1072
	v_lshlrev_b32_e32 v48, 16, v166
	v_mul_f32_e32 v32, v32, v48
	v_and_b32_e32 v48, 0xffff0000, v166
	v_mul_f32_e32 v33, v33, v48
	v_lshlrev_b32_e32 v48, 16, v167
	v_mul_f32_e32 v34, v34, v48
	v_and_b32_e32 v48, 0xffff0000, v167
	v_mul_f32_e32 v35, v35, v48
	v_cvt_pk_bf16_f32 v32, v32, v33
	v_cvt_pk_bf16_f32 v33, v34, v35
	global_store_dwordx2 v[50:51], v[32:33], off offset:1088
	v_lshlrev_b32_e32 v32, 16, v164
	v_fma_f32 v33, v72, v36, v178
	v_mul_f32_e32 v32, v33, v32
	v_and_b32_e32 v33, 0xffff0000, v164
	v_fma_f32 v34, v73, v37, v178
	v_mul_f32_e32 v33, v34, v33
	v_lshlrev_b32_e32 v34, 16, v165
	v_fma_f32 v35, v74, v38, v178
	v_mul_f32_e32 v34, v35, v34
	v_and_b32_e32 v35, 0xffff0000, v165
	v_fma_f32 v36, v75, v39, v178
	v_mul_f32_e32 v35, v36, v35
	v_cvt_pk_bf16_f32 v32, v32, v33
	v_cvt_pk_bf16_f32 v33, v34, v35
	global_store_dwordx2 v[50:51], v[32:33], off offset:1104
	v_lshlrev_b32_e32 v32, 16, v162
	v_fma_f32 v33, v68, v40, v178
	v_mul_f32_e32 v32, v33, v32
	v_and_b32_e32 v33, 0xffff0000, v162
	v_fma_f32 v34, v69, v41, v178
	v_mul_f32_e32 v33, v34, v33
	v_lshlrev_b32_e32 v34, 16, v163
	v_fma_f32 v35, v70, v42, v178
	v_mul_f32_e32 v34, v35, v34
	v_and_b32_e32 v35, 0xffff0000, v163
	v_fma_f32 v36, v71, v43, v178
	v_mul_f32_e32 v35, v36, v35
	v_cvt_pk_bf16_f32 v32, v32, v33
	v_cvt_pk_bf16_f32 v33, v34, v35
	global_store_dwordx2 v[50:51], v[32:33], off offset:1120
	v_lshlrev_b32_e32 v32, 16, v160
	v_fma_f32 v33, v64, v44, v178
	v_mul_f32_e32 v32, v33, v32
	v_and_b32_e32 v33, 0xffff0000, v160
	v_fma_f32 v34, v65, v45, v178
	v_mul_f32_e32 v33, v34, v33
	v_lshlrev_b32_e32 v34, 16, v161
	v_fma_f32 v35, v66, v46, v178
	v_mul_f32_e32 v34, v35, v34
	v_and_b32_e32 v35, 0xffff0000, v161
	v_fmac_f32_e32 v178, v67, v47
	v_mul_f32_e32 v35, v178, v35
	v_cvt_pk_bf16_f32 v32, v32, v33
	v_cvt_pk_bf16_f32 v33, v34, v35
	v_lshlrev_b32_e32 v34, 16, v158
	v_fma_f32 v16, v92, v16, v177
	global_store_dwordx2 v[50:51], v[32:33], off offset:1136
	v_or_b32_e32 v32, 32, v96
	v_mul_f32_e32 v16, v16, v34
	v_and_b32_e32 v34, 0xffff0000, v158
	v_fma_f32 v17, v93, v17, v177
	v_ashrrev_i32_e32 v33, 31, v32
	v_mul_f32_e32 v17, v17, v34
	v_lshlrev_b32_e32 v34, 16, v159
	v_fma_f32 v18, v94, v18, v177
	v_lshlrev_b64 v[32:33], 11, v[32:33]
	v_mul_f32_e32 v18, v18, v34
	v_and_b32_e32 v34, 0xffff0000, v159
	v_fma_f32 v19, v95, v19, v177
	v_lshl_add_u64 v[32:33], s[6:7], 0, v[32:33]
	v_mul_f32_e32 v19, v19, v34
	v_cvt_pk_bf16_f32 v16, v16, v17
	v_cvt_pk_bf16_f32 v17, v18, v19
	v_lshl_add_u64 v[18:19], v[32:33], 0, v[196:197]
	global_store_dwordx2 v[18:19], v[16:17], off offset:1024
	v_lshlrev_b32_e32 v16, 16, v156
	v_fma_f32 v17, v88, v20, v177
	v_mul_f32_e32 v16, v17, v16
	v_and_b32_e32 v17, 0xffff0000, v156
	v_fma_f32 v20, v89, v21, v177
	v_mul_f32_e32 v17, v20, v17
	v_lshlrev_b32_e32 v20, 16, v157
	v_fma_f32 v21, v90, v22, v177
	v_mul_f32_e32 v20, v21, v20
	v_and_b32_e32 v21, 0xffff0000, v157
	v_fma_f32 v22, v91, v23, v177
	v_mul_f32_e32 v21, v22, v21
	v_cvt_pk_bf16_f32 v16, v16, v17
	v_cvt_pk_bf16_f32 v17, v20, v21
	global_store_dwordx2 v[18:19], v[16:17], off offset:1040
	v_lshlrev_b32_e32 v16, 16, v154
	v_fma_f32 v17, v84, v24, v177
	v_mul_f32_e32 v16, v17, v16
	v_and_b32_e32 v17, 0xffff0000, v154
	v_fma_f32 v20, v85, v25, v177
	v_mul_f32_e32 v17, v20, v17
	v_lshlrev_b32_e32 v20, 16, v155
	v_fma_f32 v21, v86, v26, v177
	v_mul_f32_e32 v20, v21, v20
	v_and_b32_e32 v21, 0xffff0000, v155
	v_fma_f32 v22, v87, v27, v177
	v_mul_f32_e32 v21, v22, v21
	v_cvt_pk_bf16_f32 v16, v16, v17
	v_cvt_pk_bf16_f32 v17, v20, v21
	global_store_dwordx2 v[18:19], v[16:17], off offset:1056
	v_lshlrev_b32_e32 v16, 16, v152
	v_fma_f32 v17, v80, v28, v177
	v_mul_f32_e32 v16, v17, v16
	v_and_b32_e32 v17, 0xffff0000, v152
	v_fma_f32 v20, v81, v29, v177
	v_mul_f32_e32 v17, v20, v17
	v_lshlrev_b32_e32 v20, 16, v153
	v_fma_f32 v21, v82, v30, v177
	v_mul_f32_e32 v20, v21, v20
	v_and_b32_e32 v21, 0xffff0000, v153
	v_fma_f32 v22, v83, v31, v177
	v_cvt_pk_bf16_f32 v16, v16, v17
	v_mul_f32_e32 v21, v22, v21
	v_cvt_pk_bf16_f32 v17, v20, v21
	global_store_dwordx2 v[18:19], v[16:17], off offset:1072
	v_lshlrev_b32_e32 v16, 16, v150
	v_fma_f32 v0, v76, v0, v177
	v_mul_f32_e32 v0, v0, v16
	v_and_b32_e32 v16, 0xffff0000, v150
	v_fma_f32 v1, v77, v1, v177
	v_mul_f32_e32 v1, v1, v16
	v_lshlrev_b32_e32 v16, 16, v151
	v_fma_f32 v2, v78, v2, v177
	v_mul_f32_e32 v2, v2, v16
	v_and_b32_e32 v16, 0xffff0000, v151
	v_fma_f32 v3, v79, v3, v177
	v_mul_f32_e32 v3, v3, v16
	v_cvt_pk_bf16_f32 v0, v0, v1
	v_cvt_pk_bf16_f32 v1, v2, v3
	global_store_dwordx2 v[18:19], v[0:1], off offset:1088
	v_lshlrev_b32_e32 v0, 16, v148
	v_fma_f32 v1, v72, v4, v177
	v_mul_f32_e32 v0, v1, v0
	v_and_b32_e32 v1, 0xffff0000, v148
	v_fma_f32 v2, v73, v5, v177
	v_mul_f32_e32 v1, v2, v1
	v_lshlrev_b32_e32 v2, 16, v149
	v_fma_f32 v3, v74, v6, v177
	v_mul_f32_e32 v2, v3, v2
	v_and_b32_e32 v3, 0xffff0000, v149
	v_fma_f32 v4, v75, v7, v177
	v_mul_f32_e32 v3, v4, v3
	v_cvt_pk_bf16_f32 v0, v0, v1
	v_cvt_pk_bf16_f32 v1, v2, v3
	global_store_dwordx2 v[18:19], v[0:1], off offset:1104
	v_lshlrev_b32_e32 v0, 16, v146
	v_fma_f32 v1, v68, v8, v177
	v_mul_f32_e32 v0, v1, v0
	v_and_b32_e32 v1, 0xffff0000, v146
	v_fma_f32 v2, v69, v9, v177
	v_mul_f32_e32 v1, v2, v1
	v_lshlrev_b32_e32 v2, 16, v147
	v_fma_f32 v3, v70, v10, v177
	v_mul_f32_e32 v2, v3, v2
	v_and_b32_e32 v3, 0xffff0000, v147
	v_fma_f32 v4, v71, v11, v177
	v_mul_f32_e32 v3, v4, v3
	v_cvt_pk_bf16_f32 v0, v0, v1
	v_cvt_pk_bf16_f32 v1, v2, v3
	global_store_dwordx2 v[18:19], v[0:1], off offset:1120
	v_lshlrev_b32_e32 v0, 16, v144
	v_fma_f32 v1, v64, v12, v177
	v_mul_f32_e32 v0, v1, v0
	v_and_b32_e32 v1, 0xffff0000, v144
	v_fma_f32 v2, v65, v13, v177
	v_readlane_b32 s3, v250, 19
	v_mul_f32_e32 v1, v2, v1
	v_lshlrev_b32_e32 v2, 16, v145
	v_fma_f32 v3, v66, v14, v177
	s_add_i32 s1, s1, s3
	v_mul_f32_e32 v2, v3, v2
	v_and_b32_e32 v3, 0xffff0000, v145
	v_fmac_f32_e32 v177, v67, v15
	s_cmpk_lt_i32 s2, 0x100
	v_mul_f32_e32 v3, v177, v3
	v_cvt_pk_bf16_f32 v0, v0, v1
	v_cvt_pk_bf16_f32 v1, v2, v3
	global_store_dwordx2 v[18:19], v[0:1], off offset:1136
	s_barrier
	s_cbranch_scc0 .LBB0_701
.LBB0_681:
	v_mov_b32_e32 v20, v199
	v_mov_b32_e32 v0, s1
	s_movk_i32 s3, 0x7f
	s_and_b32 s8, s2, 1
	v_bfi_b32 v2, s3, v20, v0
	s_waitcnt lgkmcnt(0)
	v_mov_b64_e32 v[0:1], s[82:83]
	v_mad_i64_i32 v[0:1], s[6:7], v2, s94, v[0:1]
	s_lshl_b32 s36, s8, 9
	v_lshl_add_u64 v[0:1], v[0:1], 0, s[36:37]
	v_lshrrev_b32_e32 v176, 7, v20
	v_mov_b32_e32 v177, 0
	v_lshlrev_b32_e32 v176, 6, v176
	v_add_u32_e32 v60, 8, v176
	v_add_u32_e32 v58, 16, v176
	v_add_u32_e32 v56, 24, v176
	v_add_u32_e32 v54, 32, v176
	v_add_u32_e32 v52, 40, v176
	v_add_u32_e32 v50, 48, v176
	v_add_u32_e32 v48, 56, v176
	s_and_b32 s3, s1, 0xffffff80
	v_readfirstlane_b32 vcc_lo, v20
	s_cmp_lt_u32 vcc_lo, 0x80
	s_cbranch_scc0 .Lsgu_noss
	v_add_u32_e32 v246, s3, v20
	v_readlane_b32 s12, v249, 13
	v_ashrrev_i32_e32 v247, 31, v246
	v_readlane_b32 s13, v249, 14
	v_lshlrev_b64 v[246:247], 6, v[246:247]
	s_nop 0
	v_lshl_add_u64 v[246:247], s[12:13], 0, v[246:247]
	global_load_dwordx4 v[234:237], v[246:247], off
	global_load_dwordx4 v[238:241], v[246:247], off offset:16
	global_load_dwordx4 v[242:245], v[246:247], off offset:32
	global_load_dwordx2 v[254:255], v[246:247], off offset:48
	global_load_dwordx2 v[246:247], v[246:247], off offset:56
.Lsgu_noss:
	v_lshl_add_u64 v[2:3], v[176:177], 1, v[0:1]
	global_load_dwordx4 v[44:47], v[2:3], off offset:2560
	global_load_dwordx4 v[36:39], v[2:3], off offset:2576
	global_load_dwordx4 v[32:35], v[2:3], off offset:2592
	global_load_dwordx4 v[16:19], v[2:3], off offset:2608
	global_load_dwordx4 v[12:15], v[2:3], off offset:2624
	global_load_dwordx4 v[8:11], v[2:3], off offset:2640
	global_load_dwordx4 v[4:7], v[2:3], off offset:2656
	global_load_dwordx4 v[0:3], v[2:3], off offset:2672
	v_readfirstlane_b32 s9, v20
	s_mov_b64 s[6:7], exec
	s_branch .LBB0_680
